# v19 plus s_setprio 1/0 around the four MFMA clusters of the differential attention loop
# speedup vs baseline: 1.0064x; 1.0044x over previous
; #define MFMA32(a, b, c) __builtin_amdgcn_mfma_f32_32x32x16_bf16((a), (b), (c), 0, 0, 0)
; DI bool soft_core(f32x16& s, float base, float slope2, bool boundary, int tmk8, int wlim, float& mref, bool& seen, float& l, float& alpha) {
;     const float b0 = base - mref;
; #pragma unroll
;     for (int j = 0; j < 16; ++j) s[j] = fmaf(s[j], C1, fmaf(slope2, (float)(16 * (j >> 3) + (j & 7)), b0));
;     if (boundary) {
; #pragma unroll
;         for (int j = 0; j < 16; ++j) { const int d = tmk8 - (16 * (j >> 3) + (j & 7)); s[j] = (d >= 0 && d < wlim) ? s[j] : -INFINITY; }
; DI void diff_block(const bf16_t* QK, const bf16_t* VT, bf16_t* O, const float* subln, const unsigned* kmx, float lam, int b, int h, int tqb, int wave, int lane, unsigned char* lds) {
;     ...
;         const bool a0 = kb <= tq0, a1 = kb + 32 <= tq0;
;         if (a0) {
;             f32x16 s1 = zero16(), s0 = zero16();
;             if (a1) {
; #pragma unroll
;                 for (int ks = 0; ks < 4; ++ks) s1 = MFMA32(*(const bf16x8*)(B1 + kfo + ks * 32), qf[ks], s1); }
; #pragma unroll
;             for (int ks = 0; ks < 4; ++ks) s0 = MFMA32(*(const bf16x8*)(B0 + kfo + ks * 32), qf[ks], s0);
;             float alpha;
;             if (a1) {
;                 const int tmk = t - kb - 32;
;                 if (soft_core(s1, -slope2 * (float)(tmk - 8 * hf), slope2, kb + 32 == tq0, tmk - 8 * hf, 1 << 30, m, seen, l, alpha)) {
.LBB0_315:
	s_or_b64 exec, exec, s[0:1]
	v_add_u32_e32 v0, 64, v183
	v_cmp_le_u32_e64 s[8:9], v0, v184
	s_and_saveexec_b64 s[62:63], s[8:9]
	s_cbranch_execz .LBB0_339
	s_mul_i32 s0, s74, 0x9800
	s_add_i32 s75, s0, 0
	v_cmp_ge_u32_e32 vcc, v0, v184
	v_cmp_lt_u32_e64 s[0:1], v0, v184
	v_add_u32_e32 v0, s75, v167
	ds_read_b128 v[190:193], v0
	ds_read_b128 v[194:197], v0 offset:32
	ds_read_b128 v[198:201], v0 offset:64
	ds_read_b128 v[202:205], v0 offset:96
	s_and_saveexec_b64 s[2:3], s[0:1]
	s_cbranch_execz .LBB0_318
	ds_read_b128 v[206:209], v0 offset:19456
	ds_read_b128 v[210:213], v0 offset:19488
	ds_read_b128 v[214:217], v0 offset:19520
	ds_read_b128 v[218:221], v0 offset:19552
	s_waitcnt lgkmcnt(3)
	s_setprio 1
	v_mfma_f32_32x32x16_bf16 v[96:111], v[206:209], v[112:115], 0
	s_waitcnt lgkmcnt(2)
	v_mfma_f32_32x32x16_bf16 v[96:111], v[210:213], v[116:119], v[96:111]
	s_waitcnt lgkmcnt(1)
	v_mfma_f32_32x32x16_bf16 v[96:111], v[214:217], v[120:123], v[96:111]
	s_waitcnt lgkmcnt(0)
	v_mfma_f32_32x32x16_bf16 v[96:111], v[218:221], v[124:127], v[96:111]
	s_setprio 0
.LBB0_318:
	s_or_b64 exec, exec, s[2:3]
	s_waitcnt lgkmcnt(0)
	s_setprio 1
	v_mfma_f32_32x32x16_bf16 v[80:95], v[190:193], v[112:115], 0
	v_mfma_f32_32x32x16_bf16 v[80:95], v[194:197], v[116:119], v[80:95]
	v_mfma_f32_32x32x16_bf16 v[80:95], v[198:201], v[120:123], v[80:95]
	v_mfma_f32_32x32x16_bf16 v[80:95], v[202:205], v[124:127], v[80:95]
	s_setprio 0
	s_and_saveexec_b64 s[0:1], vcc
	s_xor_b64 s[0:1], exec, s[0:1]
	v_add_u32_e32 v187, s73, v174
	s_or_saveexec_b64 s[0:1], s[0:1]
	s_add_i32 s64, s42, s73
	s_mov_b64 s[2:3], s[54:55]
	s_xor_b64 exec, exec, s[0:1]
	s_cbranch_execz .LBB0_329
	v_add_u32_e32 v0, s75, v172
	ds_read_b128 v[222:225], v0 offset:28672
	ds_read_b128 v[226:229], v0 offset:28704
	ds_read_b128 v[230:233], v0 offset:31232
	ds_read_b128 v[234:237], v0 offset:31264
	ds_read_b128 v[238:241], v0 offset:33792
	ds_read_b128 v[242:245], v0 offset:33824
	ds_read_b128 v[206:209], v0 offset:36352
	ds_read_b128 v[210:213], v0 offset:36384
	v_add_u32_e32 v187, s73, v174
	v_add_u32_e32 v0, 0xffffffa0, v187
	v_cvt_f32_i32_e32 v2, v0
	s_cmpk_lg_i32 s64, 0x60
	v_fma_f32 v4, -v158, v2, -v186
	v_fma_f32 v2, 0, v158, v4
	v_add_f32_e32 v3, v158, v4
	v_pk_fma_f32 v[10:11], v[96:97], s[12:13], v[2:3] op_sel_hi:[1,0,1]
	v_pk_fma_f32 v[2:3], v[158:159], s[28:29], v[4:5] op_sel_hi:[1,1,0]
	v_pk_fma_f32 v[6:7], v[158:159], s[26:27], v[4:5] op_sel_hi:[1,1,0]
	v_pk_fma_f32 v[12:13], v[100:101], s[12:13], v[2:3] op_sel_hi:[1,0,1]
	v_pk_fma_f32 v[2:3], v[158:159], s[30:31], v[4:5] op_sel_hi:[1,1,0]
	v_pk_fma_f32 v[8:9], v[98:99], s[12:13], v[6:7] op_sel_hi:[1,0,1]
	v_pk_fma_f32 v[14:15], v[102:103], s[12:13], v[2:3] op_sel_hi:[1,0,1]
	v_pk_fma_f32 v[2:3], v[158:159], s[34:35], v[4:5] op_sel_hi:[1,1,0]
	s_nop 0
	v_pk_fma_f32 v[96:97], v[104:105], s[12:13], v[2:3] op_sel_hi:[1,0,1]
	v_pk_fma_f32 v[2:3], v[158:159], s[36:37], v[4:5] op_sel_hi:[1,1,0]
	s_nop 0
	v_pk_fma_f32 v[6:7], v[106:107], s[12:13], v[2:3] op_sel_hi:[1,0,1]
	v_pk_fma_f32 v[2:3], v[158:159], s[46:47], v[4:5] op_sel_hi:[1,1,0]
	v_pk_fma_f32 v[4:5], v[158:159], s[48:49], v[4:5] op_sel_hi:[1,1,0]
	v_pk_fma_f32 v[2:3], v[108:109], s[12:13], v[2:3] op_sel_hi:[1,0,1]
	v_pk_fma_f32 v[4:5], v[110:111], s[12:13], v[4:5] op_sel_hi:[1,0,1]
	s_cbranch_scc1 .LBB0_323
	v_add_u32_e32 v98, 0xffffff9f, v187
	v_cmp_gt_u32_e32 vcc, 2.0, v0
	v_add_u32_e32 v99, -2, v0
	v_add_u32_e32 v100, -3, v0
	v_cndmask_b32_e32 v10, v180, v10, vcc
	v_cmp_gt_u32_e32 vcc, 2.0, v98
	v_add_u32_e32 v101, -4, v0
	v_add_u32_e32 v102, -5, v0
	v_cndmask_b32_e32 v11, v180, v11, vcc
	v_cmp_gt_u32_e32 vcc, 2.0, v99
	v_add_u32_e32 v103, -6, v0
	v_add_u32_e32 v104, -7, v0
	v_cndmask_b32_e32 v8, v180, v8, vcc
	v_cmp_gt_u32_e32 vcc, 2.0, v100
	v_add_u32_e32 v105, -16, v0
	v_subrev_u32_e32 v106, 17, v0
	v_cndmask_b32_e32 v9, v180, v9, vcc
	v_cmp_gt_u32_e32 vcc, 2.0, v101
	v_subrev_u32_e32 v107, 18, v0
	v_subrev_u32_e32 v108, 19, v0
	v_cndmask_b32_e32 v12, v180, v12, vcc
	v_cmp_gt_u32_e32 vcc, 2.0, v102
	v_subrev_u32_e32 v109, 20, v0
	v_subrev_u32_e32 v110, 21, v0
	v_cndmask_b32_e32 v13, v180, v13, vcc
	v_cmp_gt_u32_e32 vcc, 2.0, v103
	v_subrev_u32_e32 v111, 22, v0
	v_subrev_u32_e32 v188, 23, v0
	v_cndmask_b32_e32 v14, v180, v14, vcc
	v_cmp_gt_u32_e32 vcc, 2.0, v104
	s_nop 1
	v_cndmask_b32_e32 v15, v180, v15, vcc
	v_cmp_gt_u32_e32 vcc, 2.0, v105
	s_nop 1
	v_cndmask_b32_e32 v96, v180, v96, vcc
	v_cmp_gt_u32_e32 vcc, 2.0, v106
	s_nop 1
	v_cndmask_b32_e32 v97, v180, v97, vcc
	v_cmp_gt_u32_e32 vcc, 2.0, v107
	s_nop 1
	v_cndmask_b32_e32 v6, v180, v6, vcc
	v_cmp_gt_u32_e32 vcc, 2.0, v108
	s_nop 1
	v_cndmask_b32_e32 v7, v180, v7, vcc
	v_cmp_gt_u32_e32 vcc, 2.0, v109
	s_nop 1
	v_cndmask_b32_e32 v2, v180, v2, vcc
	v_cmp_gt_u32_e32 vcc, 2.0, v110
	s_nop 1
	v_cndmask_b32_e32 v3, v180, v3, vcc
	v_cmp_gt_u32_e32 vcc, 2.0, v111
	s_nop 1
	v_cndmask_b32_e32 v4, v180, v4, vcc
	v_cmp_gt_u32_e32 vcc, 2.0, v188
	s_nop 1
	v_cndmask_b32_e32 v5, v180, v5, vcc

; #define MFMA32(a, b, c) __builtin_amdgcn_mfma_f32_32x32x16_bf16((a), (b), (c), 0, 0, 0)
; DI float fexp2(float x) { return __builtin_amdgcn_exp2f(x); }
; DI bool soft_core(f32x16& s, float base, float slope2, bool boundary, int tmk8, int wlim, float& mref, bool& seen, float& l, float& alpha) {
;     ...
;     seen = seen || valid;
;     float sum = 0.f;
; #pragma unroll
;     for (int j = 0; j < 16; ++j) { s[j] = fexp2(s[j]); sum += s[j]; }
;     l += sum;
; DI void diff_block(const bf16_t* QK, const bf16_t* VT, bf16_t* O, const float* subln, const unsigned* kmx, float lam, int b, int h, int tqb, int wave, int lane, unsigned char* lds) {
;     ...
;                 const bf16x8 p0 = pack8(s1[0], s1[1], s1[2], s1[3], s1[4], s1[5], s1[6], s1[7]), p1 = pack8(s1[8], s1[9], s1[10], s1[11], s1[12], s1[13], s1[14], s1[15]);
; #pragma unroll
;                 for (int dt = 0; dt < 4; ++dt) { o[dt] = MFMA32(*(const bf16x8*)(B1 + vfo + dt * (32 * 80)), p0, o[dt]); o[dt] = MFMA32(*(const bf16x8*)(B1 + vfo + dt * (32 * 80) + 32), p1, o[dt]); }
.LBB0_328:
	v_exp_f32_e32 v0, v10
	v_exp_f32_e32 v100, v11
	v_exp_f32_e32 v101, v8
	v_exp_f32_e32 v102, v9
	v_exp_f32_e32 v103, v12
	v_exp_f32_e32 v104, v13
	v_exp_f32_e32 v105, v14
	v_exp_f32_e32 v106, v15
	v_exp_f32_e32 v107, v96
	v_exp_f32_e32 v108, v97
	v_cvt_pk_bf16_f32 v12, v0, v100
	v_cvt_pk_bf16_f32 v13, v101, v102
	v_cvt_pk_bf16_f32 v14, v103, v104
	v_cvt_pk_bf16_f32 v15, v105, v106
	v_exp_f32_e32 v110, v6
	s_waitcnt lgkmcnt(0)
	s_setprio 1
	v_mfma_f32_32x32x16_bf16 v[64:79], v[222:225], v[12:15], v[64:79]
	v_exp_f32_e32 v111, v7
	v_exp_f32_e32 v188, v2
	v_exp_f32_e32 v10, v3
	v_exp_f32_e32 v11, v4
	v_exp_f32_e32 v189, v5
	v_cvt_pk_bf16_f32 v2, v107, v108
	v_cvt_pk_bf16_f32 v3, v110, v111
	v_cvt_pk_bf16_f32 v4, v188, v10
	v_cvt_pk_bf16_f32 v5, v11, v189
	v_add_f32_e32 v0, 0, v0
	v_add_f32_e32 v0, v100, v0
	v_mfma_f32_32x32x16_bf16 v[64:79], v[226:229], v[2:5], v[64:79]
	v_add_f32_e32 v0, v101, v0
	v_add_f32_e32 v0, v102, v0
	v_add_f32_e32 v0, v103, v0
	v_add_f32_e32 v0, v104, v0
	v_add_f32_e32 v0, v105, v0
	v_add_f32_e32 v0, v106, v0
	v_mfma_f32_32x32x16_bf16 v[48:63], v[230:233], v[12:15], v[48:63]
	v_add_f32_e32 v0, v107, v0
	v_add_f32_e32 v0, v108, v0
	v_add_f32_e32 v0, v110, v0
	v_add_f32_e32 v0, v111, v0
	v_add_f32_e32 v0, v188, v0
	v_add_f32_e32 v0, v10, v0
	v_mfma_f32_32x32x16_bf16 v[48:63], v[234:237], v[2:5], v[48:63]
	s_or_b64 s[2:3], s[54:55], s[10:11]
	v_add_f32_e32 v0, v11, v0
	v_add_f32_e32 v0, v189, v0
	s_andn2_b64 s[10:11], s[54:55], exec
	s_and_b64 s[2:3], s[2:3], exec
	v_add_f32_e32 v155, v155, v0
	v_mfma_f32_32x32x16_bf16 v[32:47], v[238:241], v[12:15], v[32:47]
	s_or_b64 s[2:3], s[10:11], s[2:3]
	v_mfma_f32_32x32x16_bf16 v[32:47], v[242:245], v[2:5], v[32:47]
	v_mfma_f32_32x32x16_bf16 v[16:31], v[206:209], v[12:15], v[16:31]
	v_mfma_f32_32x32x16_bf16 v[16:31], v[210:213], v[2:5], v[16:31]
	s_setprio 0

; #define MFMA32(a, b, c) __builtin_amdgcn_mfma_f32_32x32x16_bf16((a), (b), (c), 0, 0, 0)
; DI void diff_block(const bf16_t* QK, const bf16_t* VT, bf16_t* O, const float* subln, const unsigned* kmx, float lam, int b, int h, int tqb, int wave, int lane, unsigned char* lds) {
;     ...
;                 if (soft_core(s0, -slope2 * (float)(tmk - 8 * hf), slope2, kb == tq0, tmk - 8 * hf, 1 << 30, m, seen, l, alpha)) {
; #pragma unroll
;                     for (int dt = 0; dt < 4; ++dt) o[dt] *= alpha; }
;                 const bf16x8 p0 = pack8(s0[0], s0[1], s0[2], s0[3], s0[4], s0[5], s0[6], s0[7]), p1 = pack8(s0[8], s0[9], s0[10], s0[11], s0[12], s0[13], s0[14], s0[15]);
; #pragma unroll
;                 for (int dt = 0; dt < 4; ++dt) { o[dt] = MFMA32(*(const bf16x8*)(B0 + vfo + dt * (32 * 80)), p0, o[dt]); o[dt] = MFMA32(*(const bf16x8*)(B0 + vfo + dt * (32 * 80) + 32), p1, o[dt]); }
.LBB0_336:
	v_exp_f32_e32 v0, v10
	v_exp_f32_e32 v84, v11
	v_exp_f32_e32 v85, v8
	v_exp_f32_e32 v86, v9
	v_exp_f32_e32 v87, v12
	v_exp_f32_e32 v88, v13
	v_exp_f32_e32 v89, v14
	v_exp_f32_e32 v90, v15
	v_exp_f32_e32 v91, v80
	v_exp_f32_e32 v92, v81
	v_cvt_pk_bf16_f32 v12, v0, v84
	v_cvt_pk_bf16_f32 v13, v85, v86
	v_cvt_pk_bf16_f32 v14, v87, v88
	v_cvt_pk_bf16_f32 v15, v89, v90
	v_exp_f32_e32 v94, v6
	s_waitcnt lgkmcnt(0)
	s_setprio 1
	v_mfma_f32_32x32x16_bf16 v[64:79], v[222:225], v[12:15], v[64:79]
	v_exp_f32_e32 v95, v7
	v_exp_f32_e32 v96, v2
	v_exp_f32_e32 v10, v3
	v_exp_f32_e32 v11, v4
	v_exp_f32_e32 v97, v5
	v_cvt_pk_bf16_f32 v2, v91, v92
	v_cvt_pk_bf16_f32 v3, v94, v95
	v_cvt_pk_bf16_f32 v4, v96, v10
	v_cvt_pk_bf16_f32 v5, v11, v97
	v_add_f32_e32 v0, 0, v0
	v_add_f32_e32 v0, v84, v0
	v_mfma_f32_32x32x16_bf16 v[64:79], v[226:229], v[2:5], v[64:79]
	v_add_f32_e32 v0, v85, v0
	v_add_f32_e32 v0, v86, v0
	v_add_f32_e32 v0, v87, v0
	v_add_f32_e32 v0, v88, v0
	v_add_f32_e32 v0, v89, v0
	v_add_f32_e32 v0, v90, v0
	v_mfma_f32_32x32x16_bf16 v[48:63], v[230:233], v[12:15], v[48:63]
	v_add_f32_e32 v0, v91, v0
	v_add_f32_e32 v0, v92, v0
	v_add_f32_e32 v0, v94, v0
	v_add_f32_e32 v0, v95, v0
	v_add_f32_e32 v0, v96, v0
	v_add_f32_e32 v0, v10, v0
	v_mfma_f32_32x32x16_bf16 v[48:63], v[234:237], v[2:5], v[48:63]
	s_or_b64 s[0:1], s[2:3], s[10:11]
	v_add_f32_e32 v0, v11, v0
	v_add_f32_e32 v0, v97, v0
	s_andn2_b64 s[2:3], s[54:55], exec
	s_and_b64 s[0:1], s[0:1], exec
	v_add_f32_e32 v155, v155, v0
	v_mfma_f32_32x32x16_bf16 v[32:47], v[238:241], v[12:15], v[32:47]
	s_or_b64 s[54:55], s[2:3], s[0:1]
	v_mfma_f32_32x32x16_bf16 v[32:47], v[242:245], v[2:5], v[32:47]
	v_mfma_f32_32x32x16_bf16 v[16:31], v[206:209], v[12:15], v[16:31]
	v_mfma_f32_32x32x16_bf16 v[16:31], v[210:213], v[2:5], v[16:31]
	s_setprio 0
	s_or_b64 exec, exec, s[62:63]
	s_and_saveexec_b64 s[0:1], s[6:7]
	s_cbranch_execnz .LBB0_340
